# attention loop: P1-first PV order, 6-VALU MFMA gaps; no barrier after FF2(l0); rest-tail conversion
# speedup vs baseline: 1.0283x; 1.0030x over previous
.Lam_loop:
	s_waitcnt vmcnt(3)
	s_barrier
	s_add_u32 m0, s82, 0x18000
	v_lshl_add_u64 v[152:153], v[142:143], 0, s[84:85]
	global_load_lds_dwordx4 v[152:153], off
	s_add_u32 m0, s82, 0x18400
	v_lshl_add_u64 v[152:153], v[144:145], 0, s[84:85]
	global_load_lds_dwordx4 v[152:153], off
	s_add_u32 m0, s83, 0x1c000
	v_lshl_add_u64 v[152:153], v[140:141], 0, s[86:87]
	global_load_lds_dwordx4 v[152:153], off
	s_add_u32 m0, s82, 0x1e000
	v_lshl_add_u64 v[152:153], v[142:143], 0, s[88:89]
	global_load_lds_dwordx4 v[152:153], off
	s_add_u32 m0, s82, 0x1e400
	v_lshl_add_u64 v[152:153], v[144:145], 0, s[88:89]
	global_load_lds_dwordx4 v[152:153], off
	s_add_u32 m0, s83, 0x22000
	v_lshl_add_u64 v[152:153], v[140:141], 0, s[90:91]
	global_load_lds_dwordx4 v[152:153], off
	s_add_u32 s84, s84, 0x30000
	s_addc_u32 s85, s85, 0
	s_add_u32 s88, s88, 0x30000
	s_addc_u32 s89, s89, 0
	s_add_u32 s86, s86, 0x100
	s_addc_u32 s87, s87, 0
	s_add_u32 s90, s90, 0x100
	s_addc_u32 s91, s91, 0
	s_cmp_eq_u32 s92, 0
	s_cselect_b32 s93, 0, 0xfffe8000
	s_mov_b32 s92, 1
	v_add_u32_e32 v242, s93, v242
	v_add_u32_e32 v243, s93, v243
	v_add_u32_e32 v244, s93, v244
	v_add_u32_e32 v245, s93, v245
	v_add_u32_e32 v246, s93, v246
	v_add_u32_e32 v247, s93, v247
	v_add_u32_e32 v248, s93, v248
	v_add_u32_e32 v249, s93, v249
	ds_read_b128 v[90:93], v243 offset:16384
	ds_read_b128 v[148:151], v247 offset:16384
	s_waitcnt lgkmcnt(7)
	v_mfma_f32_32x32x16_bf16 v[48:63], v[218:221], v[66:69], 0
	ds_read_b128 v[218:221], v94 offset:24576
	v_max3_f32 v152, v32, v33, v34
	v_max3_f32 v153, v35, v36, v37
	v_max3_f32 v152, v152, v38, v39
	v_max3_f32 v153, v153, v40, v41
	v_max3_f32 v152, v152, v42, v43
	v_max3_f32 v153, v153, v44, v45
	s_waitcnt lgkmcnt(7)
	v_mfma_f32_32x32x16_bf16 v[48:63], v[222:225], v[70:73], v[48:63]
	ds_read_b128 v[222:225], v95 offset:24576
	v_max3_f32 v152, v152, v46, v47
	v_max_f32_e32 v152, v152, v153
	v_mov_b32_e32 v153, v152
	s_nop 1
	v_permlane32_swap_b32_e32 v153, v152
	v_max_f32_e32 v152, v152, v153
	v_add_f32_e32 v153, 0x41000000, v217
	v_cmp_lt_f32_e32 vcc, v153, v152
	s_cbranch_vccnz .Lam_c0u0_rare
.Lam_c0u0_back:
	s_waitcnt lgkmcnt(7)
	v_mfma_f32_32x32x16_bf16 v[48:63], v[226:229], v[74:77], v[48:63]
	ds_read_b128 v[226:229], v97 offset:24576
	v_sub_f32_e32 v40, v40, v217
	v_sub_f32_e32 v41, v41, v217
	v_sub_f32_e32 v42, v42, v217
	v_sub_f32_e32 v43, v43, v217
	v_exp_f32_e32 v40, v40
	v_exp_f32_e32 v41, v41
	s_waitcnt lgkmcnt(7)
	v_mfma_f32_32x32x16_bf16 v[48:63], v[230:233], v[78:81], v[48:63]
	ds_read_b128 v[230:233], v147 offset:24576
	v_exp_f32_e32 v42, v42
	v_exp_f32_e32 v43, v43
	v_sub_f32_e32 v44, v44, v217
	v_sub_f32_e32 v45, v45, v217
	v_sub_f32_e32 v46, v46, v217
	v_sub_f32_e32 v47, v47, v217
	s_waitcnt lgkmcnt(7)
	v_mfma_f32_32x32x16_bf16 v[48:63], v[234:237], v[82:85], v[48:63]
	ds_read_b128 v[234:237], v242 offset:16384
	v_exp_f32_e32 v44, v44
	v_exp_f32_e32 v45, v45
	v_exp_f32_e32 v46, v46
	v_exp_f32_e32 v47, v47
	v_add_f32_e32 v153, v40, v42
	v_add_f32_e32 v152, v41, v43
	s_waitcnt lgkmcnt(7)
	v_mfma_f32_32x32x16_bf16 v[48:63], v[238:241], v[86:89], v[48:63]
	ds_read_b128 v[238:241], v246 offset:16384
	v_add_f32_e32 v153, v153, v44
	v_add_f32_e32 v152, v152, v45
	v_add_f32_e32 v153, v153, v46
	v_add_f32_e32 v152, v152, v47
	v_cvt_pk_bf16_f32 v40, v40, v41
	v_cvt_pk_bf16_f32 v41, v42, v43
	v_cvt_pk_bf16_f32 v42, v44, v45
	v_cvt_pk_bf16_f32 v43, v46, v47
	s_nop 1
	s_waitcnt lgkmcnt(7)
	v_mfma_f32_32x32x16_bf16 v[0:15], v[90:93], v[40:43], v[0:15]
	v_sub_f32_e32 v32, v32, v217
	v_sub_f32_e32 v33, v33, v217
	v_sub_f32_e32 v34, v34, v217
	v_sub_f32_e32 v35, v35, v217
	v_exp_f32_e32 v32, v32
	v_exp_f32_e32 v33, v33
	v_exp_f32_e32 v34, v34
	v_exp_f32_e32 v35, v35
	s_waitcnt lgkmcnt(6)
	v_mfma_f32_32x32x16_bf16 v[16:31], v[148:151], v[40:43], v[16:31]
	v_sub_f32_e32 v36, v36, v217
	v_sub_f32_e32 v37, v37, v217
	v_sub_f32_e32 v38, v38, v217
	v_sub_f32_e32 v39, v39, v217
	v_exp_f32_e32 v36, v36
	v_exp_f32_e32 v37, v37
	v_exp_f32_e32 v38, v38
	v_exp_f32_e32 v39, v39
	v_add_f32_e32 v153, v153, v32
	v_add_f32_e32 v152, v152, v33
	v_add_f32_e32 v153, v153, v34
	v_add_f32_e32 v152, v152, v35
	v_add_f32_e32 v153, v153, v36
	v_add_f32_e32 v152, v152, v37
	v_add_f32_e32 v153, v153, v38
	v_add_f32_e32 v152, v152, v39
	v_cvt_pk_bf16_f32 v32, v32, v33
	v_cvt_pk_bf16_f32 v33, v34, v35
	v_cvt_pk_bf16_f32 v34, v36, v37
	v_cvt_pk_bf16_f32 v35, v38, v39
	v_add_f32_e32 v153, v153, v152
	v_add_f32_e32 v96, v96, v153
	s_nop 0
	s_waitcnt lgkmcnt(1)
	v_mfma_f32_32x32x16_bf16 v[0:15], v[234:237], v[32:35], v[0:15]
	ds_read_b128 v[234:237], v200 offset:24576
	s_waitcnt lgkmcnt(1)
	v_mfma_f32_32x32x16_bf16 v[16:31], v[238:241], v[32:35], v[16:31]
	ds_read_b128 v[238:241], v201 offset:24576
	ds_read_b128 v[90:93], v245 offset:16384
	ds_read_b128 v[148:151], v249 offset:16384
	v_mfma_f32_32x32x16_bf16 v[32:47], v[218:221], v[66:69], 0
	ds_read_b128 v[218:221], v94 offset:32768
	v_max3_f32 v152, v48, v49, v50
	v_max3_f32 v153, v51, v52, v53
	v_max3_f32 v152, v152, v54, v55
	v_max3_f32 v153, v153, v56, v57
	v_max3_f32 v152, v152, v58, v59
	v_max3_f32 v153, v153, v60, v61
	v_mfma_f32_32x32x16_bf16 v[32:47], v[222:225], v[70:73], v[32:47]
	ds_read_b128 v[222:225], v95 offset:32768
	v_max3_f32 v152, v152, v62, v63
	v_max_f32_e32 v152, v152, v153
	v_mov_b32_e32 v153, v152
	s_nop 1
	v_permlane32_swap_b32_e32 v153, v152
	v_max_f32_e32 v152, v152, v153
	v_add_f32_e32 v153, 0x41000000, v217
	v_cmp_lt_f32_e32 vcc, v153, v152
	s_cbranch_vccnz .Lam_c0u1_rare
.Lam_c0u1_back:
	v_mfma_f32_32x32x16_bf16 v[32:47], v[226:229], v[74:77], v[32:47]
	ds_read_b128 v[226:229], v97 offset:32768
	v_sub_f32_e32 v56, v56, v217
	v_sub_f32_e32 v57, v57, v217
	v_sub_f32_e32 v58, v58, v217
	v_sub_f32_e32 v59, v59, v217
	v_exp_f32_e32 v56, v56
	v_exp_f32_e32 v57, v57
	v_mfma_f32_32x32x16_bf16 v[32:47], v[230:233], v[78:81], v[32:47]
	ds_read_b128 v[230:233], v147 offset:32768
	v_exp_f32_e32 v58, v58
	v_exp_f32_e32 v59, v59
	v_sub_f32_e32 v60, v60, v217
	v_sub_f32_e32 v61, v61, v217
	v_sub_f32_e32 v62, v62, v217
	v_sub_f32_e32 v63, v63, v217
	s_waitcnt lgkmcnt(7)
	v_mfma_f32_32x32x16_bf16 v[32:47], v[234:237], v[82:85], v[32:47]
	ds_read_b128 v[234:237], v244 offset:16384
	v_exp_f32_e32 v60, v60
	v_exp_f32_e32 v61, v61
	v_exp_f32_e32 v62, v62
	v_exp_f32_e32 v63, v63
	v_add_f32_e32 v153, v56, v58
	v_add_f32_e32 v152, v57, v59
	s_waitcnt lgkmcnt(7)
	v_mfma_f32_32x32x16_bf16 v[32:47], v[238:241], v[86:89], v[32:47]
	ds_read_b128 v[238:241], v248 offset:16384
	v_add_f32_e32 v153, v153, v60
	v_add_f32_e32 v152, v152, v61
	v_add_f32_e32 v153, v153, v62
	v_add_f32_e32 v152, v152, v63
	v_cvt_pk_bf16_f32 v56, v56, v57
	v_cvt_pk_bf16_f32 v57, v58, v59
	v_cvt_pk_bf16_f32 v58, v60, v61
	v_cvt_pk_bf16_f32 v59, v62, v63
	s_nop 1
	s_waitcnt lgkmcnt(7)
	v_mfma_f32_32x32x16_bf16 v[0:15], v[90:93], v[56:59], v[0:15]
	v_sub_f32_e32 v48, v48, v217
	v_sub_f32_e32 v49, v49, v217
	v_sub_f32_e32 v50, v50, v217
	v_sub_f32_e32 v51, v51, v217
	v_exp_f32_e32 v48, v48
	v_exp_f32_e32 v49, v49
	v_exp_f32_e32 v50, v50
	v_exp_f32_e32 v51, v51
	s_waitcnt lgkmcnt(6)
	v_mfma_f32_32x32x16_bf16 v[16:31], v[148:151], v[56:59], v[16:31]
	v_sub_f32_e32 v52, v52, v217
	v_sub_f32_e32 v53, v53, v217
	v_sub_f32_e32 v54, v54, v217
	v_sub_f32_e32 v55, v55, v217
	v_exp_f32_e32 v52, v52
	v_exp_f32_e32 v53, v53
	v_exp_f32_e32 v54, v54
	v_exp_f32_e32 v55, v55
	v_add_f32_e32 v153, v153, v48
	v_add_f32_e32 v152, v152, v49
	v_add_f32_e32 v153, v153, v50
	v_add_f32_e32 v152, v152, v51
	v_add_f32_e32 v153, v153, v52
	v_add_f32_e32 v152, v152, v53
	v_add_f32_e32 v153, v153, v54
	v_add_f32_e32 v152, v152, v55
	v_cvt_pk_bf16_f32 v48, v48, v49
	v_cvt_pk_bf16_f32 v49, v50, v51
	v_cvt_pk_bf16_f32 v50, v52, v53
	v_cvt_pk_bf16_f32 v51, v54, v55
	v_add_f32_e32 v153, v153, v152
	v_add_f32_e32 v96, v96, v153
	s_nop 0
	s_waitcnt lgkmcnt(1)
	v_mfma_f32_32x32x16_bf16 v[0:15], v[234:237], v[48:51], v[0:15]
	ds_read_b128 v[234:237], v200 offset:32768
	s_waitcnt lgkmcnt(1)
	v_mfma_f32_32x32x16_bf16 v[16:31], v[238:241], v[48:51], v[16:31]
	ds_read_b128 v[238:241], v201 offset:32768
	v_add_u32_e32 v94, 0xc000, v94
	v_add_u32_e32 v95, 0xc000, v95
	v_add_u32_e32 v97, 0xc000, v97
	v_add_u32_e32 v147, 0xc000, v147
	v_add_u32_e32 v200, 0xc000, v200
	v_add_u32_e32 v201, 0xc000, v201
	ds_read_b128 v[90:93], v243 offset:40960
	ds_read_b128 v[148:151], v247 offset:40960
	v_mfma_f32_32x32x16_bf16 v[48:63], v[218:221], v[66:69], 0
	ds_read_b128 v[218:221], v94
	v_max3_f32 v152, v32, v33, v34
	v_max3_f32 v153, v35, v36, v37
	v_max3_f32 v152, v152, v38, v39
	v_max3_f32 v153, v153, v40, v41
	v_max3_f32 v152, v152, v42, v43
	v_max3_f32 v153, v153, v44, v45
	v_mfma_f32_32x32x16_bf16 v[48:63], v[222:225], v[70:73], v[48:63]
	ds_read_b128 v[222:225], v95
	v_max3_f32 v152, v152, v46, v47
	v_max_f32_e32 v152, v152, v153
	v_mov_b32_e32 v153, v152
	s_nop 1
	v_permlane32_swap_b32_e32 v153, v152
	v_max_f32_e32 v152, v152, v153
	v_add_f32_e32 v153, 0x41000000, v217
	v_cmp_lt_f32_e32 vcc, v153, v152
	s_cbranch_vccnz .Lam_c0u2_rare
.Lam_c0u2_back:
	v_mfma_f32_32x32x16_bf16 v[48:63], v[226:229], v[74:77], v[48:63]
	ds_read_b128 v[226:229], v97
	v_sub_f32_e32 v40, v40, v217
	v_sub_f32_e32 v41, v41, v217
	v_sub_f32_e32 v42, v42, v217
	v_sub_f32_e32 v43, v43, v217
	v_exp_f32_e32 v40, v40
	v_exp_f32_e32 v41, v41
	v_mfma_f32_32x32x16_bf16 v[48:63], v[230:233], v[78:81], v[48:63]
	ds_read_b128 v[230:233], v147
	v_exp_f32_e32 v42, v42
	v_exp_f32_e32 v43, v43
	v_sub_f32_e32 v44, v44, v217
	v_sub_f32_e32 v45, v45, v217
	v_sub_f32_e32 v46, v46, v217
	v_sub_f32_e32 v47, v47, v217
	s_waitcnt lgkmcnt(7)
	v_mfma_f32_32x32x16_bf16 v[48:63], v[234:237], v[82:85], v[48:63]
	ds_read_b128 v[234:237], v242 offset:40960
	v_exp_f32_e32 v44, v44
	v_exp_f32_e32 v45, v45
	v_exp_f32_e32 v46, v46
	v_exp_f32_e32 v47, v47
	v_add_f32_e32 v153, v40, v42
	v_add_f32_e32 v152, v41, v43
	s_waitcnt lgkmcnt(7)
	v_mfma_f32_32x32x16_bf16 v[48:63], v[238:241], v[86:89], v[48:63]
	ds_read_b128 v[238:241], v246 offset:40960
	v_add_f32_e32 v153, v153, v44
	v_add_f32_e32 v152, v152, v45
	v_add_f32_e32 v153, v153, v46
	v_add_f32_e32 v152, v152, v47
	v_cvt_pk_bf16_f32 v40, v40, v41
	v_cvt_pk_bf16_f32 v41, v42, v43
	v_cvt_pk_bf16_f32 v42, v44, v45
	v_cvt_pk_bf16_f32 v43, v46, v47
	s_nop 1
	s_waitcnt lgkmcnt(7)
	v_mfma_f32_32x32x16_bf16 v[0:15], v[90:93], v[40:43], v[0:15]
	v_sub_f32_e32 v32, v32, v217
	v_sub_f32_e32 v33, v33, v217
	v_sub_f32_e32 v34, v34, v217
	v_sub_f32_e32 v35, v35, v217
	v_exp_f32_e32 v32, v32
	v_exp_f32_e32 v33, v33
	v_exp_f32_e32 v34, v34
	v_exp_f32_e32 v35, v35
	s_waitcnt lgkmcnt(6)
	v_mfma_f32_32x32x16_bf16 v[16:31], v[148:151], v[40:43], v[16:31]
	v_sub_f32_e32 v36, v36, v217
	v_sub_f32_e32 v37, v37, v217
	v_sub_f32_e32 v38, v38, v217
	v_sub_f32_e32 v39, v39, v217
	v_exp_f32_e32 v36, v36
	v_exp_f32_e32 v37, v37
	v_exp_f32_e32 v38, v38
	v_exp_f32_e32 v39, v39
	v_add_f32_e32 v153, v153, v32
	v_add_f32_e32 v152, v152, v33
	v_add_f32_e32 v153, v153, v34
	v_add_f32_e32 v152, v152, v35
	v_add_f32_e32 v153, v153, v36
	v_add_f32_e32 v152, v152, v37
	v_add_f32_e32 v153, v153, v38
	v_add_f32_e32 v152, v152, v39
	v_cvt_pk_bf16_f32 v32, v32, v33
	v_cvt_pk_bf16_f32 v33, v34, v35
	v_cvt_pk_bf16_f32 v34, v36, v37
	v_cvt_pk_bf16_f32 v35, v38, v39
	v_add_f32_e32 v153, v153, v152
	v_add_f32_e32 v96, v96, v153
	s_nop 0
	s_waitcnt lgkmcnt(1)
	v_mfma_f32_32x32x16_bf16 v[0:15], v[234:237], v[32:35], v[0:15]
	ds_read_b128 v[234:237], v200
	s_waitcnt lgkmcnt(1)
	v_mfma_f32_32x32x16_bf16 v[16:31], v[238:241], v[32:35], v[16:31]
	ds_read_b128 v[238:241], v201
	ds_read_b128 v[90:93], v245 offset:40960
	ds_read_b128 v[148:151], v249 offset:40960
	v_mfma_f32_32x32x16_bf16 v[32:47], v[218:221], v[66:69], 0
	ds_read_b128 v[218:221], v94 offset:8192
	v_max3_f32 v152, v48, v49, v50
	v_max3_f32 v153, v51, v52, v53
	v_max3_f32 v152, v152, v54, v55
	v_max3_f32 v153, v153, v56, v57
	v_max3_f32 v152, v152, v58, v59
	v_max3_f32 v153, v153, v60, v61
	v_mfma_f32_32x32x16_bf16 v[32:47], v[222:225], v[70:73], v[32:47]
	ds_read_b128 v[222:225], v95 offset:8192
	v_max3_f32 v152, v152, v62, v63
	v_max_f32_e32 v152, v152, v153
	v_mov_b32_e32 v153, v152
	s_nop 1
	v_permlane32_swap_b32_e32 v153, v152
	v_max_f32_e32 v152, v152, v153
	v_add_f32_e32 v153, 0x41000000, v217
	v_cmp_lt_f32_e32 vcc, v153, v152
	s_cbranch_vccnz .Lam_c0u3_rare
.Lam_c0u3_back:
	v_mfma_f32_32x32x16_bf16 v[32:47], v[226:229], v[74:77], v[32:47]
	ds_read_b128 v[226:229], v97 offset:8192
	v_sub_f32_e32 v56, v56, v217
	v_sub_f32_e32 v57, v57, v217
	v_sub_f32_e32 v58, v58, v217
	v_sub_f32_e32 v59, v59, v217
	v_exp_f32_e32 v56, v56
	v_exp_f32_e32 v57, v57
	v_mfma_f32_32x32x16_bf16 v[32:47], v[230:233], v[78:81], v[32:47]
	ds_read_b128 v[230:233], v147 offset:8192
	v_exp_f32_e32 v58, v58
	v_exp_f32_e32 v59, v59
	v_sub_f32_e32 v60, v60, v217
	v_sub_f32_e32 v61, v61, v217
	v_sub_f32_e32 v62, v62, v217
	v_sub_f32_e32 v63, v63, v217
	s_waitcnt lgkmcnt(7)
	v_mfma_f32_32x32x16_bf16 v[32:47], v[234:237], v[82:85], v[32:47]
	ds_read_b128 v[234:237], v244 offset:40960
	v_exp_f32_e32 v60, v60
	v_exp_f32_e32 v61, v61
	v_exp_f32_e32 v62, v62
	v_exp_f32_e32 v63, v63
	v_add_f32_e32 v153, v56, v58
	v_add_f32_e32 v152, v57, v59
	s_waitcnt lgkmcnt(7)
	v_mfma_f32_32x32x16_bf16 v[32:47], v[238:241], v[86:89], v[32:47]
	ds_read_b128 v[238:241], v248 offset:40960
	v_add_f32_e32 v153, v153, v60
	v_add_f32_e32 v152, v152, v61
	v_add_f32_e32 v153, v153, v62
	v_add_f32_e32 v152, v152, v63
	v_cvt_pk_bf16_f32 v56, v56, v57
	v_cvt_pk_bf16_f32 v57, v58, v59
	v_cvt_pk_bf16_f32 v58, v60, v61
	v_cvt_pk_bf16_f32 v59, v62, v63
	s_nop 1
	s_waitcnt lgkmcnt(7)
	v_mfma_f32_32x32x16_bf16 v[0:15], v[90:93], v[56:59], v[0:15]
	v_sub_f32_e32 v48, v48, v217
	v_sub_f32_e32 v49, v49, v217
	v_sub_f32_e32 v50, v50, v217
	v_sub_f32_e32 v51, v51, v217
	v_exp_f32_e32 v48, v48
	v_exp_f32_e32 v49, v49
	v_exp_f32_e32 v50, v50
	v_exp_f32_e32 v51, v51
	s_waitcnt lgkmcnt(6)
	v_mfma_f32_32x32x16_bf16 v[16:31], v[148:151], v[56:59], v[16:31]
	v_sub_f32_e32 v52, v52, v217
	v_sub_f32_e32 v53, v53, v217
	v_sub_f32_e32 v54, v54, v217
	v_sub_f32_e32 v55, v55, v217
	v_exp_f32_e32 v52, v52
	v_exp_f32_e32 v53, v53
	v_exp_f32_e32 v54, v54
	v_exp_f32_e32 v55, v55
	v_add_f32_e32 v153, v153, v48
	v_add_f32_e32 v152, v152, v49
	v_add_f32_e32 v153, v153, v50
	v_add_f32_e32 v152, v152, v51
	v_add_f32_e32 v153, v153, v52
	v_add_f32_e32 v152, v152, v53
	v_add_f32_e32 v153, v153, v54
	v_add_f32_e32 v152, v152, v55
	v_cvt_pk_bf16_f32 v48, v48, v49
	v_cvt_pk_bf16_f32 v49, v50, v51
	v_cvt_pk_bf16_f32 v50, v52, v53
	v_cvt_pk_bf16_f32 v51, v54, v55
	v_add_f32_e32 v153, v153, v152
	v_add_f32_e32 v96, v96, v153
	s_nop 0
	s_waitcnt lgkmcnt(1)
	v_mfma_f32_32x32x16_bf16 v[0:15], v[234:237], v[48:51], v[0:15]
	ds_read_b128 v[234:237], v200 offset:8192
	s_waitcnt lgkmcnt(1)
	v_mfma_f32_32x32x16_bf16 v[16:31], v[238:241], v[48:51], v[16:31]
	ds_read_b128 v[238:241], v201 offset:8192
	s_add_i32 s81, s81, -1
	s_cmp_eq_u32 s81, 0
	s_cbranch_scc1 .Lam_exit
	s_waitcnt vmcnt(3)
	s_barrier
	s_add_u32 m0, s82, 0x0
	v_lshl_add_u64 v[152:153], v[142:143], 0, s[84:85]
	global_load_lds_dwordx4 v[152:153], off
	s_add_u32 m0, s82, 0x400
	v_lshl_add_u64 v[152:153], v[144:145], 0, s[84:85]
	global_load_lds_dwordx4 v[152:153], off
	s_add_u32 m0, s83, 0x4000
	v_lshl_add_u64 v[152:153], v[140:141], 0, s[86:87]
	global_load_lds_dwordx4 v[152:153], off
	s_add_u32 m0, s82, 0x6000
	v_lshl_add_u64 v[152:153], v[142:143], 0, s[88:89]
	global_load_lds_dwordx4 v[152:153], off
	s_add_u32 m0, s82, 0x6400
	v_lshl_add_u64 v[152:153], v[144:145], 0, s[88:89]
	global_load_lds_dwordx4 v[152:153], off
	s_add_u32 m0, s83, 0xa000
	v_lshl_add_u64 v[152:153], v[140:141], 0, s[90:91]
	global_load_lds_dwordx4 v[152:153], off
	s_add_u32 s84, s84, 0x30000
	s_addc_u32 s85, s85, 0
	s_add_u32 s88, s88, 0x30000
	s_addc_u32 s89, s89, 0
	s_add_u32 s86, s86, 0x100
	s_addc_u32 s87, s87, 0
	s_add_u32 s90, s90, 0x100
	s_addc_u32 s91, s91, 0
	v_add_u32_e32 v242, 0xc000, v242
	v_add_u32_e32 v243, 0xc000, v243
	v_add_u32_e32 v244, 0xc000, v244
	v_add_u32_e32 v245, 0xc000, v245
	v_add_u32_e32 v246, 0xc000, v246
	v_add_u32_e32 v247, 0xc000, v247
	v_add_u32_e32 v248, 0xc000, v248
	v_add_u32_e32 v249, 0xc000, v249
	ds_read_b128 v[90:93], v243 offset:16384
	ds_read_b128 v[148:151], v247 offset:16384
	v_mfma_f32_32x32x16_bf16 v[48:63], v[218:221], v[66:69], 0
	ds_read_b128 v[218:221], v94 offset:24576
	v_max3_f32 v152, v32, v33, v34
	v_max3_f32 v153, v35, v36, v37
	v_max3_f32 v152, v152, v38, v39
	v_max3_f32 v153, v153, v40, v41
	v_max3_f32 v152, v152, v42, v43
	v_max3_f32 v153, v153, v44, v45
	v_mfma_f32_32x32x16_bf16 v[48:63], v[222:225], v[70:73], v[48:63]
	ds_read_b128 v[222:225], v95 offset:24576
	v_max3_f32 v152, v152, v46, v47
	v_max_f32_e32 v152, v152, v153
	v_mov_b32_e32 v153, v152
	s_nop 1
	v_permlane32_swap_b32_e32 v153, v152
	v_max_f32_e32 v152, v152, v153
	v_add_f32_e32 v153, 0x41000000, v217
	v_cmp_lt_f32_e32 vcc, v153, v152
	s_cbranch_vccnz .Lam_c1u0_rare
.Lam_c1u0_back:
	v_mfma_f32_32x32x16_bf16 v[48:63], v[226:229], v[74:77], v[48:63]
	ds_read_b128 v[226:229], v97 offset:24576
	v_sub_f32_e32 v40, v40, v217
	v_sub_f32_e32 v41, v41, v217
	v_sub_f32_e32 v42, v42, v217
	v_sub_f32_e32 v43, v43, v217
	v_exp_f32_e32 v40, v40
	v_exp_f32_e32 v41, v41
	v_mfma_f32_32x32x16_bf16 v[48:63], v[230:233], v[78:81], v[48:63]
	ds_read_b128 v[230:233], v147 offset:24576
	v_exp_f32_e32 v42, v42
	v_exp_f32_e32 v43, v43
	v_sub_f32_e32 v44, v44, v217
	v_sub_f32_e32 v45, v45, v217
	v_sub_f32_e32 v46, v46, v217
	v_sub_f32_e32 v47, v47, v217
	s_waitcnt lgkmcnt(7)
	v_mfma_f32_32x32x16_bf16 v[48:63], v[234:237], v[82:85], v[48:63]
	ds_read_b128 v[234:237], v242 offset:16384
	v_exp_f32_e32 v44, v44
	v_exp_f32_e32 v45, v45
	v_exp_f32_e32 v46, v46
	v_exp_f32_e32 v47, v47
	v_add_f32_e32 v153, v40, v42
	v_add_f32_e32 v152, v41, v43
	s_waitcnt lgkmcnt(7)
	v_mfma_f32_32x32x16_bf16 v[48:63], v[238:241], v[86:89], v[48:63]
	ds_read_b128 v[238:241], v246 offset:16384
	v_add_f32_e32 v153, v153, v44
	v_add_f32_e32 v152, v152, v45
	v_add_f32_e32 v153, v153, v46
	v_add_f32_e32 v152, v152, v47
	v_cvt_pk_bf16_f32 v40, v40, v41
	v_cvt_pk_bf16_f32 v41, v42, v43
	v_cvt_pk_bf16_f32 v42, v44, v45
	v_cvt_pk_bf16_f32 v43, v46, v47
	s_nop 1
	s_waitcnt lgkmcnt(7)
	v_mfma_f32_32x32x16_bf16 v[0:15], v[90:93], v[40:43], v[0:15]
	v_sub_f32_e32 v32, v32, v217
	v_sub_f32_e32 v33, v33, v217
	v_sub_f32_e32 v34, v34, v217
	v_sub_f32_e32 v35, v35, v217
	v_exp_f32_e32 v32, v32
	v_exp_f32_e32 v33, v33
	v_exp_f32_e32 v34, v34
	v_exp_f32_e32 v35, v35
	s_waitcnt lgkmcnt(6)
	v_mfma_f32_32x32x16_bf16 v[16:31], v[148:151], v[40:43], v[16:31]
	v_sub_f32_e32 v36, v36, v217
	v_sub_f32_e32 v37, v37, v217
	v_sub_f32_e32 v38, v38, v217
	v_sub_f32_e32 v39, v39, v217
	v_exp_f32_e32 v36, v36
	v_exp_f32_e32 v37, v37
	v_exp_f32_e32 v38, v38
	v_exp_f32_e32 v39, v39
	v_add_f32_e32 v153, v153, v32
	v_add_f32_e32 v152, v152, v33
	v_add_f32_e32 v153, v153, v34
	v_add_f32_e32 v152, v152, v35
	v_add_f32_e32 v153, v153, v36
	v_add_f32_e32 v152, v152, v37
	v_add_f32_e32 v153, v153, v38
	v_add_f32_e32 v152, v152, v39
	v_cvt_pk_bf16_f32 v32, v32, v33
	v_cvt_pk_bf16_f32 v33, v34, v35
	v_cvt_pk_bf16_f32 v34, v36, v37
	v_cvt_pk_bf16_f32 v35, v38, v39
	v_add_f32_e32 v153, v153, v152
	v_add_f32_e32 v96, v96, v153
	s_nop 0
	s_waitcnt lgkmcnt(1)
	v_mfma_f32_32x32x16_bf16 v[0:15], v[234:237], v[32:35], v[0:15]
	ds_read_b128 v[234:237], v200 offset:24576
	s_waitcnt lgkmcnt(1)
	v_mfma_f32_32x32x16_bf16 v[16:31], v[238:241], v[32:35], v[16:31]
	ds_read_b128 v[238:241], v201 offset:24576
	ds_read_b128 v[90:93], v245 offset:16384
	ds_read_b128 v[148:151], v249 offset:16384
	v_mfma_f32_32x32x16_bf16 v[32:47], v[218:221], v[66:69], 0
	ds_read_b128 v[218:221], v94 offset:32768
	v_max3_f32 v152, v48, v49, v50
	v_max3_f32 v153, v51, v52, v53
	v_max3_f32 v152, v152, v54, v55
	v_max3_f32 v153, v153, v56, v57
	v_max3_f32 v152, v152, v58, v59
	v_max3_f32 v153, v153, v60, v61
	v_mfma_f32_32x32x16_bf16 v[32:47], v[222:225], v[70:73], v[32:47]
	ds_read_b128 v[222:225], v95 offset:32768
	v_max3_f32 v152, v152, v62, v63
	v_max_f32_e32 v152, v152, v153
	v_mov_b32_e32 v153, v152
	s_nop 1
	v_permlane32_swap_b32_e32 v153, v152
	v_max_f32_e32 v152, v152, v153
	v_add_f32_e32 v153, 0x41000000, v217
	v_cmp_lt_f32_e32 vcc, v153, v152
	s_cbranch_vccnz .Lam_c1u1_rare

.Lam_c1u3_back:
	v_mfma_f32_32x32x16_bf16 v[32:47], v[226:229], v[74:77], v[32:47]
	ds_read_b128 v[226:229], v97 offset:8192
	v_sub_f32_e32 v56, v56, v217
	v_sub_f32_e32 v57, v57, v217
	v_sub_f32_e32 v58, v58, v217
	v_sub_f32_e32 v59, v59, v217
	v_exp_f32_e32 v56, v56
	v_exp_f32_e32 v57, v57
	v_mfma_f32_32x32x16_bf16 v[32:47], v[230:233], v[78:81], v[32:47]
	ds_read_b128 v[230:233], v147 offset:8192
	v_exp_f32_e32 v58, v58
	v_exp_f32_e32 v59, v59
	v_sub_f32_e32 v60, v60, v217
	v_sub_f32_e32 v61, v61, v217
	v_sub_f32_e32 v62, v62, v217
	v_sub_f32_e32 v63, v63, v217
	s_waitcnt lgkmcnt(7)
	v_mfma_f32_32x32x16_bf16 v[32:47], v[234:237], v[82:85], v[32:47]
	ds_read_b128 v[234:237], v244 offset:40960
	v_exp_f32_e32 v60, v60
	v_exp_f32_e32 v61, v61
	v_exp_f32_e32 v62, v62
	v_exp_f32_e32 v63, v63
	v_add_f32_e32 v153, v56, v58
	v_add_f32_e32 v152, v57, v59
	s_waitcnt lgkmcnt(7)
	v_mfma_f32_32x32x16_bf16 v[32:47], v[238:241], v[86:89], v[32:47]
	ds_read_b128 v[238:241], v248 offset:40960
	v_add_f32_e32 v153, v153, v60
	v_add_f32_e32 v152, v152, v61
	v_add_f32_e32 v153, v153, v62
	v_add_f32_e32 v152, v152, v63
	v_cvt_pk_bf16_f32 v56, v56, v57
	v_cvt_pk_bf16_f32 v57, v58, v59
	v_cvt_pk_bf16_f32 v58, v60, v61
	v_cvt_pk_bf16_f32 v59, v62, v63
	s_nop 1
	s_waitcnt lgkmcnt(7)
	v_mfma_f32_32x32x16_bf16 v[0:15], v[90:93], v[56:59], v[0:15]
	v_sub_f32_e32 v48, v48, v217
	v_sub_f32_e32 v49, v49, v217
	v_sub_f32_e32 v50, v50, v217
	v_sub_f32_e32 v51, v51, v217
	v_exp_f32_e32 v48, v48
	v_exp_f32_e32 v49, v49
	v_exp_f32_e32 v50, v50
	v_exp_f32_e32 v51, v51
	s_waitcnt lgkmcnt(6)
	v_mfma_f32_32x32x16_bf16 v[16:31], v[148:151], v[56:59], v[16:31]
	v_sub_f32_e32 v52, v52, v217
	v_sub_f32_e32 v53, v53, v217
	v_sub_f32_e32 v54, v54, v217
	v_sub_f32_e32 v55, v55, v217
	v_exp_f32_e32 v52, v52
	v_exp_f32_e32 v53, v53
	v_exp_f32_e32 v54, v54
	v_exp_f32_e32 v55, v55
	v_add_f32_e32 v153, v153, v48
	v_add_f32_e32 v152, v152, v49
	v_add_f32_e32 v153, v153, v50
	v_add_f32_e32 v152, v152, v51
	v_add_f32_e32 v153, v153, v52
	v_add_f32_e32 v152, v152, v53
	v_add_f32_e32 v153, v153, v54
	v_add_f32_e32 v152, v152, v55
	v_cvt_pk_bf16_f32 v48, v48, v49
	v_cvt_pk_bf16_f32 v49, v50, v51
	v_cvt_pk_bf16_f32 v50, v52, v53
	v_cvt_pk_bf16_f32 v51, v54, v55
	v_add_f32_e32 v153, v153, v152
	v_add_f32_e32 v96, v96, v153
	s_nop 0
	s_waitcnt lgkmcnt(1)
	v_mfma_f32_32x32x16_bf16 v[0:15], v[234:237], v[48:51], v[0:15]
	ds_read_b128 v[234:237], v200 offset:8192
	s_waitcnt lgkmcnt(1)
	v_mfma_f32_32x32x16_bf16 v[16:31], v[238:241], v[48:51], v[16:31]
	ds_read_b128 v[238:241], v201 offset:8192
	s_add_i32 s81, s81, -1
	s_cmp_eq_u32 s81, 0
	s_cbranch_scc1 .Lam_exit
	s_waitcnt vmcnt(3)
	s_barrier
	s_add_u32 m0, s82, 0xc000
	v_lshl_add_u64 v[152:153], v[142:143], 0, s[84:85]
	global_load_lds_dwordx4 v[152:153], off
	s_add_u32 m0, s82, 0xc400
	v_lshl_add_u64 v[152:153], v[144:145], 0, s[84:85]
	global_load_lds_dwordx4 v[152:153], off
	s_add_u32 m0, s83, 0x10000
	v_lshl_add_u64 v[152:153], v[140:141], 0, s[86:87]
	global_load_lds_dwordx4 v[152:153], off
	s_add_u32 m0, s82, 0x12000
	v_lshl_add_u64 v[152:153], v[142:143], 0, s[88:89]
	global_load_lds_dwordx4 v[152:153], off
	s_add_u32 m0, s82, 0x12400
	v_lshl_add_u64 v[152:153], v[144:145], 0, s[88:89]
	global_load_lds_dwordx4 v[152:153], off
	s_add_u32 m0, s83, 0x16000
	v_lshl_add_u64 v[152:153], v[140:141], 0, s[90:91]
	global_load_lds_dwordx4 v[152:153], off
	s_add_u32 s84, s84, 0x30000
	s_addc_u32 s85, s85, 0
	s_add_u32 s88, s88, 0x30000
	s_addc_u32 s89, s89, 0
	s_add_u32 s86, s86, 0x100
	s_addc_u32 s87, s87, 0
	s_add_u32 s90, s90, 0x100
	s_addc_u32 s91, s91, 0
	v_add_u32_e32 v242, 0xc000, v242
	v_add_u32_e32 v243, 0xc000, v243
	v_add_u32_e32 v244, 0xc000, v244
	v_add_u32_e32 v245, 0xc000, v245
	v_add_u32_e32 v246, 0xc000, v246
	v_add_u32_e32 v247, 0xc000, v247
	v_add_u32_e32 v248, 0xc000, v248
	v_add_u32_e32 v249, 0xc000, v249
	ds_read_b128 v[90:93], v243 offset:16384
	ds_read_b128 v[148:151], v247 offset:16384
	v_mfma_f32_32x32x16_bf16 v[48:63], v[218:221], v[66:69], 0
	ds_read_b128 v[218:221], v94 offset:24576
	v_max3_f32 v152, v32, v33, v34
	v_max3_f32 v153, v35, v36, v37
	v_max3_f32 v152, v152, v38, v39
	v_max3_f32 v153, v153, v40, v41
	v_max3_f32 v152, v152, v42, v43
	v_max3_f32 v153, v153, v44, v45
	v_mfma_f32_32x32x16_bf16 v[48:63], v[222:225], v[70:73], v[48:63]
	ds_read_b128 v[222:225], v95 offset:24576
	v_max3_f32 v152, v152, v46, v47
	v_max_f32_e32 v152, v152, v153
	v_mov_b32_e32 v153, v152
	s_nop 1
	v_permlane32_swap_b32_e32 v153, v152
	v_max_f32_e32 v152, v152, v153
	v_add_f32_e32 v153, 0x41000000, v217
	v_cmp_lt_f32_e32 vcc, v153, v152
	s_cbranch_vccnz .Lam_c2u0_rare

.Lam_c2u1_back:
	v_mfma_f32_32x32x16_bf16 v[32:47], v[226:229], v[74:77], v[32:47]
	ds_read_b128 v[226:229], v97 offset:32768
	v_sub_f32_e32 v56, v56, v217
	v_sub_f32_e32 v57, v57, v217
	v_sub_f32_e32 v58, v58, v217
	v_sub_f32_e32 v59, v59, v217
	v_exp_f32_e32 v56, v56
	v_exp_f32_e32 v57, v57
	v_mfma_f32_32x32x16_bf16 v[32:47], v[230:233], v[78:81], v[32:47]
	ds_read_b128 v[230:233], v147 offset:32768
	v_exp_f32_e32 v58, v58
	v_exp_f32_e32 v59, v59
	v_sub_f32_e32 v60, v60, v217
	v_sub_f32_e32 v61, v61, v217
	v_sub_f32_e32 v62, v62, v217
	v_sub_f32_e32 v63, v63, v217
	s_waitcnt lgkmcnt(7)
	v_mfma_f32_32x32x16_bf16 v[32:47], v[234:237], v[82:85], v[32:47]
	ds_read_b128 v[234:237], v244 offset:16384
	v_exp_f32_e32 v60, v60
	v_exp_f32_e32 v61, v61
	v_exp_f32_e32 v62, v62
	v_exp_f32_e32 v63, v63
	v_add_f32_e32 v153, v56, v58
	v_add_f32_e32 v152, v57, v59
	s_waitcnt lgkmcnt(7)
	v_mfma_f32_32x32x16_bf16 v[32:47], v[238:241], v[86:89], v[32:47]
	ds_read_b128 v[238:241], v248 offset:16384
	v_add_f32_e32 v153, v153, v60
	v_add_f32_e32 v152, v152, v61
	v_add_f32_e32 v153, v153, v62
	v_add_f32_e32 v152, v152, v63
	v_cvt_pk_bf16_f32 v56, v56, v57
	v_cvt_pk_bf16_f32 v57, v58, v59
	v_cvt_pk_bf16_f32 v58, v60, v61
	v_cvt_pk_bf16_f32 v59, v62, v63
	s_nop 1
	s_waitcnt lgkmcnt(7)
	v_mfma_f32_32x32x16_bf16 v[0:15], v[90:93], v[56:59], v[0:15]
	v_sub_f32_e32 v48, v48, v217
	v_sub_f32_e32 v49, v49, v217
	v_sub_f32_e32 v50, v50, v217
	v_sub_f32_e32 v51, v51, v217
	v_exp_f32_e32 v48, v48
	v_exp_f32_e32 v49, v49
	v_exp_f32_e32 v50, v50
	v_exp_f32_e32 v51, v51
	s_waitcnt lgkmcnt(6)
	v_mfma_f32_32x32x16_bf16 v[16:31], v[148:151], v[56:59], v[16:31]
	v_sub_f32_e32 v52, v52, v217
	v_sub_f32_e32 v53, v53, v217
	v_sub_f32_e32 v54, v54, v217
	v_sub_f32_e32 v55, v55, v217
	v_exp_f32_e32 v52, v52
	v_exp_f32_e32 v53, v53
	v_exp_f32_e32 v54, v54
	v_exp_f32_e32 v55, v55
	v_add_f32_e32 v153, v153, v48
	v_add_f32_e32 v152, v152, v49
	v_add_f32_e32 v153, v153, v50
	v_add_f32_e32 v152, v152, v51
	v_add_f32_e32 v153, v153, v52
	v_add_f32_e32 v152, v152, v53
	v_add_f32_e32 v153, v153, v54
	v_add_f32_e32 v152, v152, v55
	v_cvt_pk_bf16_f32 v48, v48, v49
	v_cvt_pk_bf16_f32 v49, v50, v51
	v_cvt_pk_bf16_f32 v50, v52, v53
	v_cvt_pk_bf16_f32 v51, v54, v55
	v_add_f32_e32 v153, v153, v152
	v_add_f32_e32 v96, v96, v153
	s_nop 0
	s_waitcnt lgkmcnt(1)
	v_mfma_f32_32x32x16_bf16 v[0:15], v[234:237], v[48:51], v[0:15]
	ds_read_b128 v[234:237], v200 offset:32768
	s_waitcnt lgkmcnt(1)
	v_mfma_f32_32x32x16_bf16 v[16:31], v[238:241], v[48:51], v[16:31]
	ds_read_b128 v[238:241], v201 offset:32768
	v_add_u32_e32 v94, 0xfffe8000, v94
	v_add_u32_e32 v95, 0xfffe8000, v95
	v_add_u32_e32 v97, 0xfffe8000, v97
	v_add_u32_e32 v147, 0xfffe8000, v147
	v_add_u32_e32 v200, 0xfffe8000, v200
	v_add_u32_e32 v201, 0xfffe8000, v201
	ds_read_b128 v[90:93], v243 offset:40960
	ds_read_b128 v[148:151], v247 offset:40960
	v_mfma_f32_32x32x16_bf16 v[48:63], v[218:221], v[66:69], 0
	ds_read_b128 v[218:221], v94
	v_max3_f32 v152, v32, v33, v34
	v_max3_f32 v153, v35, v36, v37
	v_max3_f32 v152, v152, v38, v39
	v_max3_f32 v153, v153, v40, v41
	v_max3_f32 v152, v152, v42, v43
	v_max3_f32 v153, v153, v44, v45
	v_mfma_f32_32x32x16_bf16 v[48:63], v[222:225], v[70:73], v[48:63]
	ds_read_b128 v[222:225], v95
	v_max3_f32 v152, v152, v46, v47
	v_max_f32_e32 v152, v152, v153
	v_mov_b32_e32 v153, v152
	s_nop 1
	v_permlane32_swap_b32_e32 v153, v152
	v_max_f32_e32 v152, v152, v153
	v_add_f32_e32 v153, 0x41000000, v217
	v_cmp_lt_f32_e32 vcc, v153, v152
	s_cbranch_vccnz .Lam_c2u2_rare

.Lam_c2u3_back:
	v_mfma_f32_32x32x16_bf16 v[32:47], v[226:229], v[74:77], v[32:47]
	ds_read_b128 v[226:229], v97 offset:8192
	v_sub_f32_e32 v56, v56, v217
	v_sub_f32_e32 v57, v57, v217
	v_sub_f32_e32 v58, v58, v217
	v_sub_f32_e32 v59, v59, v217
	v_exp_f32_e32 v56, v56
	v_exp_f32_e32 v57, v57
	v_mfma_f32_32x32x16_bf16 v[32:47], v[230:233], v[78:81], v[32:47]
	ds_read_b128 v[230:233], v147 offset:8192
	v_exp_f32_e32 v58, v58
	v_exp_f32_e32 v59, v59
	v_sub_f32_e32 v60, v60, v217
	v_sub_f32_e32 v61, v61, v217
	v_sub_f32_e32 v62, v62, v217
	v_sub_f32_e32 v63, v63, v217
	s_waitcnt lgkmcnt(7)
	v_mfma_f32_32x32x16_bf16 v[32:47], v[234:237], v[82:85], v[32:47]
	ds_read_b128 v[234:237], v244 offset:40960
	v_exp_f32_e32 v60, v60
	v_exp_f32_e32 v61, v61
	v_exp_f32_e32 v62, v62
	v_exp_f32_e32 v63, v63
	v_add_f32_e32 v153, v56, v58
	v_add_f32_e32 v152, v57, v59
	s_waitcnt lgkmcnt(7)
	v_mfma_f32_32x32x16_bf16 v[32:47], v[238:241], v[86:89], v[32:47]
	ds_read_b128 v[238:241], v248 offset:40960
	v_add_f32_e32 v153, v153, v60
	v_add_f32_e32 v152, v152, v61
	v_add_f32_e32 v153, v153, v62
	v_add_f32_e32 v152, v152, v63
	v_cvt_pk_bf16_f32 v56, v56, v57
	v_cvt_pk_bf16_f32 v57, v58, v59
	v_cvt_pk_bf16_f32 v58, v60, v61
	v_cvt_pk_bf16_f32 v59, v62, v63
	s_nop 1
	s_waitcnt lgkmcnt(7)
	v_mfma_f32_32x32x16_bf16 v[0:15], v[90:93], v[56:59], v[0:15]
	v_sub_f32_e32 v48, v48, v217
	v_sub_f32_e32 v49, v49, v217
	v_sub_f32_e32 v50, v50, v217
	v_sub_f32_e32 v51, v51, v217
	v_exp_f32_e32 v48, v48
	v_exp_f32_e32 v49, v49
	v_exp_f32_e32 v50, v50
	v_exp_f32_e32 v51, v51
	s_waitcnt lgkmcnt(6)
	v_mfma_f32_32x32x16_bf16 v[16:31], v[148:151], v[56:59], v[16:31]
	v_sub_f32_e32 v52, v52, v217
	v_sub_f32_e32 v53, v53, v217
	v_sub_f32_e32 v54, v54, v217
	v_sub_f32_e32 v55, v55, v217
	v_exp_f32_e32 v52, v52
	v_exp_f32_e32 v53, v53
	v_exp_f32_e32 v54, v54
	v_exp_f32_e32 v55, v55
	v_add_f32_e32 v153, v153, v48
	v_add_f32_e32 v152, v152, v49
	v_add_f32_e32 v153, v153, v50
	v_add_f32_e32 v152, v152, v51
	v_add_f32_e32 v153, v153, v52
	v_add_f32_e32 v152, v152, v53
	v_add_f32_e32 v153, v153, v54
	v_add_f32_e32 v152, v152, v55
	v_cvt_pk_bf16_f32 v48, v48, v49
	v_cvt_pk_bf16_f32 v49, v50, v51
	v_cvt_pk_bf16_f32 v50, v52, v53
	v_cvt_pk_bf16_f32 v51, v54, v55
	v_add_f32_e32 v153, v153, v152
	v_add_f32_e32 v96, v96, v153
	s_nop 0
	s_waitcnt lgkmcnt(1)
	v_mfma_f32_32x32x16_bf16 v[0:15], v[234:237], v[48:51], v[0:15]
	ds_read_b128 v[234:237], v200 offset:8192
	s_waitcnt lgkmcnt(1)
	v_mfma_f32_32x32x16_bf16 v[16:31], v[238:241], v[48:51], v[16:31]
	ds_read_b128 v[238:241], v201 offset:8192
	s_add_i32 s81, s81, -1
	s_cmp_eq_u32 s81, 0
	s_cbranch_scc0 .Lam_loop

.Lrp_done:
	s_cmp_eq_u32 s14, 11
	s_cbranch_scc1 .LBB0_681
	s_cmp_ge_i32 s17, s15
	s_cbranch_scc1 .LBB0_681
	v_readlane_b32 s2, v253, 13
	v_readlane_b32 s3, v253, 14
	s_andn2_b64 vcc, exec, s[2:3]
	s_cbranch_vccnz .LBB0_634
	s_waitcnt vmcnt(0)
	s_barrier
	s_mov_b64 s[2:3], exec
	v_readlane_b32 s4, v253, 53
	v_readlane_b32 s5, v253, 54
	s_and_b64 s[4:5], s[2:3], s[4:5]
	s_mov_b64 exec, s[4:5]
	s_cbranch_execz .LBB0_633
	v_readlane_b32 s4, v253, 1
	v_readlane_b32 s5, v253, 2
	buffer_wbl2 sc1
	s_load_dwordx2 s[4:5], s[4:5], 0x58
	s_mov_b64 s[6:7], exec
	v_mbcnt_lo_u32_b32 v1, s6, 0
	v_mbcnt_hi_u32_b32 v1, s7, v1
	v_cmp_eq_u32_e32 vcc, 0, v1
	s_waitcnt lgkmcnt(0)
	global_load_dword v0, v65, s[4:5] offset:40
	s_and_saveexec_b64 s[8:9], vcc
	s_cbranch_execz .LBB0_626
	s_bcnt1_i32_b64 s6, s[6:7]
	v_mov_b32_e32 v2, s6
	global_atomic_add v2, v65, v2, s[4:5] offset:32 sc0
